# v11 + GEMM loop: LDS-DMA loads use scalar-base addressing (16 VALU 64-bit adds and 4 LDS address adds per iteration removed), loop-control SALU moved behind DMA issue
# speedup vs baseline: 1.0156x; 1.0003x over previous
; #define PG8_STAGE(bufoff, gbase, voff) do { _Pragma("unroll") for (int _i = 0; _i < 2; ++_i) \
;     __builtin_amdgcn_global_load_lds((const unsigned*)((const char*)(gbase) + (voff)[_i]), (LAS unsigned*)(lds + (bufoff) + ldsw + _i * 8192), 16, 0, 0); } while (0)
; #define PG8_WAIT_V(n) asm volatile("s_waitcnt vmcnt(" #n ")" ::: "memory")
; #define PG8_BAR __builtin_amdgcn_s_barrier()
; DI void gemm_epilogue(const GemmDesc& g, f32x4 (&acc)[2][2][4][2], int brow, int bcol, int wr, int wc, int fr, int fq) {
;     ...
;       const float sc = (bcol < 1024) ? 0.0625f : 1.0f;
;       const int d0 = wc * 32 + 8 * fq;
;       float fr_[8];
; #pragma unroll
;       for (int j = 0; j < 8; ++j) fr_[j] = exp2f(-(float)(d0 + j) * (13.287712379549449f / 128.0f)) * 0.15915494309189535f;
; DI void gemm_phase(const GemmDesc& g, LAS unsigned char* lds) {
;     ...
;   PG8_STAGE(PG8_SB(0, 0), cB, voffB); PG8_STAGE(PG8_SB(0, 1), cB + hstep, voffB); PG8_STAGE(PG8_SA(0, 0), cA, voffA); PG8_STAGE(PG8_SA(0, 1), cA + hstep, voffA);
;   if (wr == 1) PG8_BAR;
;   PG8_WAIT_V(2); PG8_BAR;
;   PG8_STAGE(PG8_SB(1, 0), cB + kstep, voffB); PG8_STAGE(PG8_SA(1, 0), cA + kstep, voffA); PG8_STAGE(PG8_SB(1, 1), cB + hstep + kstep, voffB);
;   PG8_WAIT_V(6); PG8_BAR;
.LBB0_122:
	s_add_i32 m0, s73, 0x18000
	v_lshl_add_u64 v[0:1], v[0:1], 0, s[28:29]
	s_waitcnt vmcnt(2)
	s_barrier
	global_load_lds_dwordx4 v[0:1], off
	v_lshl_add_u64 v[0:1], v[2:3], 0, s[28:29]
	s_add_i32 m0, s73, 0x1a000
	s_add_i32 s95, s73, 0x8000
	global_load_lds_dwordx4 v[0:1], off
	v_lshl_add_u64 v[0:1], v[8:9], 0, s[28:29]
	s_mov_b32 m0, s95
	s_add_i32 s96, s73, 0xa000
	global_load_lds_dwordx4 v[0:1], off
	v_lshl_add_u64 v[0:1], v[10:11], 0, s[28:29]
	s_mov_b32 m0, s96
	v_lshrrev_b32_e32 v21, 1, v19
	global_load_lds_dwordx4 v[0:1], off
	s_add_i32 m0, s73, 0x1c000
	v_lshl_add_u64 v[0:1], v[4:5], 0, s[28:29]
	global_load_lds_dwordx4 v[0:1], off
	v_lshl_add_u64 v[0:1], v[6:7], 0, s[28:29]
	s_add_i32 m0, s73, 0x1e000
	v_and_b32_e32 v21, 24, v21
	global_load_lds_dwordx4 v[0:1], off
	v_and_b32_e32 v20, 15, v19
	v_lshlrev_b32_e32 v22, 1, v21
	v_lshlrev_b32_e32 v19, 2, v19
	v_lshl_or_b32 v218, s0, 6, v20
	v_lshl_or_b32 v20, v20, 6, v22
	s_lshl_b32 s0, s0, 13
	v_and_b32_e32 v19, 32, v19
	v_bitop3_b32 v22, v20, s0, v19 bitop3:0xde
	s_lshl_b32 s0, s1, 5
	s_and_b32 s0, s0, 0x60
	v_or_b32_e32 v158, s0, v21
	v_cvt_f32_ubyte0_e32 v0, v158
	s_lshl_b32 s1, s0, 7
	v_mul_f32_e32 v1, 0xbdd49a78, v0
	s_mov_b32 s0, 0xc2fc0000
	v_cmp_gt_f32_e32 vcc, s0, v1
	v_or_b32_e32 v2, 1, v158
	v_cvt_f32_ubyte0_e32 v2, v2
	v_cndmask_b32_e32 v1, 0, v216, vcc
	v_fmac_f32_e32 v1, 0xbdd49a78, v0
	v_mul_f32_e32 v3, 0xbdd49a78, v2
	v_exp_f32_e32 v0, v1
	v_cndmask_b32_e32 v1, 0, v217, vcc
	v_cmp_gt_f32_e32 vcc, s0, v3
	s_lshr_b32 s82, s26, 6
	v_ldexp_f32 v0, v0, v1
	v_cndmask_b32_e32 v3, 0, v216, vcc
	v_fmac_f32_e32 v3, 0xbdd49a78, v2
	v_exp_f32_e32 v2, v3
	v_mul_f32_e32 v220, 0.15915494, v0
	v_cndmask_b32_e32 v0, 0, v217, vcc
	s_xor_b64 s[54:55], s[84:85], -1
	v_ldexp_f32 v0, v2, v0
	v_mul_f32_e32 v221, 0.15915494, v0
	v_or_b32_e32 v0, 2, v158
	v_cvt_f32_ubyte0_e32 v0, v0
	v_mul_f32_e32 v1, 0xbdd49a78, v0
	v_cmp_gt_f32_e32 vcc, s0, v1
	v_or_b32_e32 v2, 3, v158
	v_cvt_f32_ubyte0_e32 v2, v2
	v_cndmask_b32_e32 v1, 0, v216, vcc
	v_fmac_f32_e32 v1, 0xbdd49a78, v0
	v_mul_f32_e32 v3, 0xbdd49a78, v2
	v_exp_f32_e32 v0, v1
	v_cndmask_b32_e32 v1, 0, v217, vcc
	v_cmp_gt_f32_e32 vcc, s0, v3
	s_lshr_b32 s97, s70, 4
	v_ldexp_f32 v0, v0, v1
	v_cndmask_b32_e32 v3, 0, v216, vcc
	v_fmac_f32_e32 v3, 0xbdd49a78, v2
	v_exp_f32_e32 v2, v3
	v_mul_f32_e32 v222, 0.15915494, v0
	v_cndmask_b32_e32 v0, 0, v217, vcc
	s_add_i32 s94, s82, -2
	v_ldexp_f32 v0, v2, v0
	v_mul_f32_e32 v223, 0.15915494, v0
	v_or_b32_e32 v0, 4, v158
	v_cvt_f32_ubyte0_e32 v0, v0
	v_mul_f32_e32 v1, 0xbdd49a78, v0
	v_cmp_gt_f32_e32 vcc, s0, v1
	v_or_b32_e32 v2, 5, v158
	v_cvt_f32_ubyte0_e32 v2, v2
	v_cndmask_b32_e32 v1, 0, v216, vcc
	v_fmac_f32_e32 v1, 0xbdd49a78, v0
	v_mul_f32_e32 v3, 0xbdd49a78, v2
	v_exp_f32_e32 v0, v1
	v_cndmask_b32_e32 v1, 0, v217, vcc
	v_cmp_gt_f32_e32 vcc, s0, v3
	s_cmpk_lt_u32 s4, 0x100
	v_ldexp_f32 v0, v0, v1
	v_cndmask_b32_e32 v3, 0, v216, vcc
	v_fmac_f32_e32 v3, 0xbdd49a78, v2
	v_exp_f32_e32 v2, v3
	v_mul_f32_e32 v224, 0.15915494, v0
	v_cndmask_b32_e32 v0, 0, v217, vcc
	s_cselect_b64 s[56:57], -1, 0
	v_ldexp_f32 v0, v2, v0
	v_mul_f32_e32 v225, 0.15915494, v0
	v_or_b32_e32 v0, 6, v158
	v_cvt_f32_ubyte0_e32 v0, v0
	v_mul_f32_e32 v1, 0xbdd49a78, v0
	v_cmp_gt_f32_e32 vcc, s0, v1
	v_or_b32_e32 v2, 7, v158
	v_cvt_f32_ubyte0_e32 v2, v2
	v_cndmask_b32_e32 v1, 0, v216, vcc
	v_fmac_f32_e32 v1, 0xbdd49a78, v0
	v_mul_f32_e32 v3, 0xbdd49a78, v2
	v_exp_f32_e32 v0, v1
	v_cndmask_b32_e32 v1, 0, v217, vcc
	v_cmp_gt_f32_e32 vcc, s0, v3
	s_add_u32 s0, s76, 0x1000
	v_bitop3_b32 v219, v20, s1, v19 bitop3:0xde
	v_add_u32_e32 v250, 0x10000, v219
	v_cndmask_b32_e32 v3, 0, v216, vcc
	v_fmac_f32_e32 v3, 0xbdd49a78, v2
	v_exp_f32_e32 v2, v3
	v_ldexp_f32 v0, v0, v1
	s_addc_u32 s1, s77, 0
	v_mul_f32_e32 v226, 0.15915494, v0
	v_cndmask_b32_e32 v0, 0, v217, vcc
	v_writelane_b32 v255, s0, 39
	v_ldexp_f32 v0, v2, v0
	v_mul_f32_e32 v227, 0.15915494, v0
	v_writelane_b32 v255, s1, 40
	v_rcp_iflag_f32_e32 v0, v12
	v_readlane_b32 s0, v255, 29
	s_lshl_b32 s0, -1, s0
	s_not_b32 s0, s0
	v_writelane_b32 v255, s0, 35
	v_mul_f32_e32 v0, 0x4f7ffffe, v0
	v_readlane_b32 s0, v255, 33
	v_readlane_b32 s1, v255, 34
	v_cvt_u32_f32_e32 v0, v0
	s_cmp_lg_u64 s[0:1], 0
	s_cselect_b64 s[0:1], -1, 0
	s_cmp_lg_u64 s[76:77], 0
	v_writelane_b32 v255, s0, 37
	s_cselect_b64 s[74:75], -1, 0
	s_cmp_lg_u64 s[22:23], 0
	v_writelane_b32 v255, s1, 38
	s_cselect_b64 s[58:59], -1, 0
	s_sub_i32 s0, 0, s71
	v_readfirstlane_b32 s1, v0
	v_add_u32_e32 v0, v18, v16
	s_waitcnt vmcnt(6)
	s_mul_i32 s0, s0, s1
	v_add_lshl_u32 v148, v0, v17, 1
	v_add_u32_e32 v0, v15, v13
	s_mul_hi_u32 s0, s1, s0
	v_lshl_add_u64 v[160:161], s[20:21], 0, v[148:149]
	v_add_lshl_u32 v148, v0, v14, 1
	s_mov_b32 s83, 0
	s_add_i32 s80, s1, s0
	v_lshl_add_u64 v[162:163], s[20:21], 0, v[148:149]
	v_add_u32_e32 v228, 0, v22
	s_mov_b32 s4, 0
	s_mov_b32 s81, 0
	s_barrier
	s_branch .LBB0_125

; #define PG8_STAGE(bufoff, gbase, voff) do { _Pragma("unroll") for (int _i = 0; _i < 2; ++_i) \
;     __builtin_amdgcn_global_load_lds((const unsigned*)((const char*)(gbase) + (voff)[_i]), (LAS unsigned*)(lds + (bufoff) + ldsw + _i * 8192), 16, 0, 0); } while (0)
; #define PG8_LDA(dst, b, h) do { _Pragma("unroll") for (int m = 0; m < 4; ++m) _Pragma("unroll") for (int k = 0; k < 2; ++k) dst[m][k] = *(const LAS bf16x8*)(lds + PG8_SA(b, h) + aoff + m * 2048 + k * 1024); } while (0)
; #define PG8_LDB(dst, b, h) do { _Pragma("unroll") for (int n = 0; n < 2; ++n) _Pragma("unroll") for (int k = 0; k < 2; ++k) dst[n][k] = *(const LAS bf16x8*)(lds + PG8_SB(b, h) + boff + n * 2048 + k * 1024); } while (0)
; #define PG8_MMA(ai, bj, At, Bt) do { __builtin_amdgcn_s_setprio(1); _Pragma("unroll") for (int m = 0; m < 4; ++m) _Pragma("unroll") for (int n = 0; n < 2; ++n) _Pragma("unroll") for (int k = 0; k < 2; ++k) \
;     acc[ai][bj][m][n] = __builtin_amdgcn_mfma_f32_16x16x32_bf16(Bt[n][k], At[m][k], acc[ai][bj][m][n], 0, 0, 0); __builtin_amdgcn_s_setprio(0); } while (0)
; #define PG8_WAIT_V(n) asm volatile("s_waitcnt vmcnt(" #n ")" ::: "memory")
; #define PG8_WAIT_L(n) asm volatile("s_waitcnt lgkmcnt(" #n ")" ::: "memory")
; #define PG8_BAR __builtin_amdgcn_s_barrier()
; #define PG8_SCHED __builtin_amdgcn_sched_barrier(0)
; DI void gemm_phase(const GemmDesc& g, LAS unsigned char* lds) {
;     ...
;       PG8_LDB(B0, 0, 0); PG8_LDB(B1, 0, 1); PG8_SCHED; PG8_LDA(At, 0, 0); PG8_STAGE(PG8_SA(1, 1), a1 + hstep, voffA);
;       PG8_WAIT_V(8); PG8_WAIT_L(0); PG8_BAR; PG8_MMA(0, 0, At, B0); PG8_MMA(0, 1, At, B1); PG8_BAR; PG8_SCHED;
;       PG8_LDA(At, 0, 1); PG8_STAGE(PG8_SB(0, 0), b2, voffB); PG8_STAGE(PG8_SB(0, 1), b2 + hstep, voffB); PG8_STAGE(PG8_SA(0, 0), a2, voffA);
;       PG8_WAIT_V(8); PG8_WAIT_L(0); PG8_BAR; PG8_MMA(1, 0, At, B0); PG8_MMA(1, 1, At, B1); PG8_BAR; PG8_SCHED;
.LBB0_132:
	ds_read_b128 v[128:131], v250
	ds_read_b128 v[132:135], v250 offset:1024
	ds_read_b128 v[136:139], v250 offset:2048
	ds_read_b128 v[140:143], v250 offset:3072
	ds_read_b128 v[164:167], v250 offset:16384
	ds_read_b128 v[168:171], v250 offset:17408
	ds_read_b128 v[172:175], v250 offset:18432
	ds_read_b128 v[176:179], v250 offset:19456
	s_add_i32 m0, s73, 0xc000
	ds_read_b128 v[180:183], v228
	ds_read_b128 v[184:187], v228 offset:1024
	ds_read_b128 v[188:191], v228 offset:2048
	ds_read_b128 v[192:195], v228 offset:3072
	ds_read_b128 v[196:199], v228 offset:4096
	ds_read_b128 v[200:203], v228 offset:5120
	ds_read_b128 v[230:233], v228 offset:6144
	ds_read_b128 v[234:237], v228 offset:7168
	global_load_lds_dwordx4 v162, s[26:27]
	s_add_i32 m0, s73, 0xe000
	s_nop 0
	global_load_lds_dwordx4 v160, s[26:27]
	s_add_i32 s48, s44, 2
	s_add_u32 s49, s26, 0x80
	s_addc_u32 s45, s27, 0
	s_add_i32 s51, 0, 0x10000
	s_cmp_eq_u32 s94, s44
	s_cselect_b32 s45, s63, s45
	s_cselect_b32 s44, s62, s49
	s_cselect_b32 s87, s1, s47
	s_cselect_b32 s86, s0, s46
	s_add_i32 s49, 0, 0x14000
	s_waitcnt vmcnt(8)
	s_waitcnt lgkmcnt(0)
	s_barrier
	s_setprio 1
	s_waitcnt lgkmcnt(0)
	v_mfma_f32_16x16x32_bf16 v[124:127], v[128:131], v[180:183], v[124:127]
	v_mfma_f32_16x16x32_bf16 v[120:123], v[136:139], v[180:183], v[120:123]
	v_mfma_f32_16x16x32_bf16 v[116:119], v[128:131], v[188:191], v[116:119]
	v_mfma_f32_16x16x32_bf16 v[112:115], v[136:139], v[188:191], v[112:115]
	v_mfma_f32_16x16x32_bf16 v[108:111], v[128:131], v[196:199], v[108:111]
	v_mfma_f32_16x16x32_bf16 v[104:107], v[136:139], v[196:199], v[104:107]
	v_mfma_f32_16x16x32_bf16 v[100:103], v[128:131], v[230:233], v[100:103]
	v_mfma_f32_16x16x32_bf16 v[96:99], v[136:139], v[230:233], v[96:99]
	v_mfma_f32_16x16x32_bf16 v[124:127], v[132:135], v[184:187], v[124:127]
	v_mfma_f32_16x16x32_bf16 v[120:123], v[140:143], v[184:187], v[120:123]
	v_mfma_f32_16x16x32_bf16 v[116:119], v[132:135], v[192:195], v[116:119]
	v_mfma_f32_16x16x32_bf16 v[112:115], v[140:143], v[192:195], v[112:115]
	v_mfma_f32_16x16x32_bf16 v[108:111], v[132:135], v[200:203], v[108:111]
	v_mfma_f32_16x16x32_bf16 v[104:107], v[140:143], v[200:203], v[104:107]
	v_mfma_f32_16x16x32_bf16 v[100:103], v[132:135], v[234:237], v[100:103]
	v_mfma_f32_16x16x32_bf16 v[96:99], v[140:143], v[234:237], v[96:99]
	v_mfma_f32_16x16x32_bf16 v[60:63], v[164:167], v[180:183], v[60:63]
	v_mfma_f32_16x16x32_bf16 v[56:59], v[172:175], v[180:183], v[56:59]
	v_mfma_f32_16x16x32_bf16 v[52:55], v[164:167], v[188:191], v[52:55]
	v_mfma_f32_16x16x32_bf16 v[48:51], v[172:175], v[188:191], v[48:51]
	v_mfma_f32_16x16x32_bf16 v[44:47], v[164:167], v[196:199], v[44:47]
	v_mfma_f32_16x16x32_bf16 v[40:43], v[172:175], v[196:199], v[40:43]
	v_mfma_f32_16x16x32_bf16 v[36:39], v[164:167], v[230:233], v[36:39]
	v_mfma_f32_16x16x32_bf16 v[32:35], v[172:175], v[230:233], v[32:35]
	v_mfma_f32_16x16x32_bf16 v[60:63], v[168:171], v[184:187], v[60:63]
	v_mfma_f32_16x16x32_bf16 v[56:59], v[176:179], v[184:187], v[56:59]
	v_mfma_f32_16x16x32_bf16 v[52:55], v[168:171], v[192:195], v[52:55]
	v_mfma_f32_16x16x32_bf16 v[48:51], v[176:179], v[192:195], v[48:51]
	v_mfma_f32_16x16x32_bf16 v[44:47], v[168:171], v[200:203], v[44:47]
	v_mfma_f32_16x16x32_bf16 v[40:43], v[176:179], v[200:203], v[40:43]
	v_mfma_f32_16x16x32_bf16 v[36:39], v[168:171], v[234:237], v[36:39]
	v_mfma_f32_16x16x32_bf16 v[32:35], v[176:179], v[234:237], v[32:35]
	s_setprio 0
	s_barrier
	s_add_i32 s51, s51, s72
	s_mov_b32 m0, s51
	ds_read_b128 v[180:183], v228 offset:16384
	ds_read_b128 v[184:187], v228 offset:17408
	ds_read_b128 v[188:191], v228 offset:18432
	ds_read_b128 v[192:195], v228 offset:19456
	ds_read_b128 v[196:199], v228 offset:20480
	ds_read_b128 v[200:203], v228 offset:21504
	ds_read_b128 v[230:233], v228 offset:22528
	ds_read_b128 v[234:237], v228 offset:23552
	global_load_lds_dwordx4 v152, s[86:87]
	s_mov_b64 s[98:99], s[86:87]
	s_add_i32 m0, s51, 0x2000
	s_add_u32 s86, s86, s20
	s_addc_u32 s87, s87, s21
	s_add_i32 s49, s49, s72
	global_load_lds_dwordx4 v156, s[98:99]
	s_mov_b32 m0, s49
	s_nop 0
	global_load_lds_dwordx4 v152, s[86:87]
	s_add_i32 m0, s49, 0x2000
	s_nop 0
	global_load_lds_dwordx4 v156, s[86:87]
	s_mov_b32 m0, s73
	s_nop 0
	s_mov_b64 s[100:101], s[44:45]
	global_load_lds_dwordx4 v150, s[44:45]
	s_mov_b32 m0, s60
	s_nop 0
	global_load_lds_dwordx4 v154, s[44:45]
	s_waitcnt vmcnt(8)
	s_waitcnt lgkmcnt(0)
	s_barrier
	s_setprio 1
	s_waitcnt lgkmcnt(0)
	v_mfma_f32_16x16x32_bf16 v[92:95], v[128:131], v[180:183], v[92:95]
	v_mfma_f32_16x16x32_bf16 v[88:91], v[136:139], v[180:183], v[88:91]
	v_mfma_f32_16x16x32_bf16 v[84:87], v[128:131], v[188:191], v[84:87]
	v_mfma_f32_16x16x32_bf16 v[80:83], v[136:139], v[188:191], v[80:83]
	v_mfma_f32_16x16x32_bf16 v[76:79], v[128:131], v[196:199], v[76:79]
	v_mfma_f32_16x16x32_bf16 v[72:75], v[136:139], v[196:199], v[72:75]
	v_mfma_f32_16x16x32_bf16 v[68:71], v[128:131], v[230:233], v[68:71]
	v_mfma_f32_16x16x32_bf16 v[64:67], v[136:139], v[230:233], v[64:67]
	v_mfma_f32_16x16x32_bf16 v[92:95], v[132:135], v[184:187], v[92:95]
	v_mfma_f32_16x16x32_bf16 v[88:91], v[140:143], v[184:187], v[88:91]
	v_mfma_f32_16x16x32_bf16 v[84:87], v[132:135], v[192:195], v[84:87]
	v_mfma_f32_16x16x32_bf16 v[80:83], v[140:143], v[192:195], v[80:83]
	v_mfma_f32_16x16x32_bf16 v[76:79], v[132:135], v[200:203], v[76:79]
	v_mfma_f32_16x16x32_bf16 v[72:75], v[140:143], v[200:203], v[72:75]
	v_mfma_f32_16x16x32_bf16 v[68:71], v[132:135], v[234:237], v[68:71]
	v_mfma_f32_16x16x32_bf16 v[64:67], v[140:143], v[234:237], v[64:67]
	v_mfma_f32_16x16x32_bf16 v[28:31], v[164:167], v[180:183], v[28:31]
	v_mfma_f32_16x16x32_bf16 v[24:27], v[172:175], v[180:183], v[24:27]
	v_mfma_f32_16x16x32_bf16 v[20:23], v[164:167], v[188:191], v[20:23]
	v_mfma_f32_16x16x32_bf16 v[16:19], v[172:175], v[188:191], v[16:19]
	v_mfma_f32_16x16x32_bf16 v[12:15], v[164:167], v[196:199], v[12:15]
	v_mfma_f32_16x16x32_bf16 v[8:11], v[172:175], v[196:199], v[8:11]
	v_mfma_f32_16x16x32_bf16 v[4:7], v[164:167], v[230:233], v[4:7]
	v_mfma_f32_16x16x32_bf16 v[0:3], v[172:175], v[230:233], v[0:3]
	v_mfma_f32_16x16x32_bf16 v[28:31], v[168:171], v[184:187], v[28:31]
	v_mfma_f32_16x16x32_bf16 v[24:27], v[176:179], v[184:187], v[24:27]
	v_mfma_f32_16x16x32_bf16 v[20:23], v[168:171], v[192:195], v[20:23]
	v_mfma_f32_16x16x32_bf16 v[16:19], v[176:179], v[192:195], v[16:19]
	v_mfma_f32_16x16x32_bf16 v[12:15], v[168:171], v[200:203], v[12:15]
	v_mfma_f32_16x16x32_bf16 v[8:11], v[176:179], v[200:203], v[8:11]
	v_mfma_f32_16x16x32_bf16 v[4:7], v[168:171], v[234:237], v[4:7]
	v_mfma_f32_16x16x32_bf16 v[0:3], v[176:179], v[234:237], v[0:3]
	s_setprio 0
	s_barrier
; #define PG8_STAGE(bufoff, gbase, voff) do { _Pragma("unroll") for (int _i = 0; _i < 2; ++_i) \
;     __builtin_amdgcn_global_load_lds((const unsigned*)((const char*)(gbase) + (voff)[_i]), (LAS unsigned*)(lds + (bufoff) + ldsw + _i * 8192), 16, 0, 0); } while (0)
; #define PG8_LDA(dst, b, h) do { _Pragma("unroll") for (int m = 0; m < 4; ++m) _Pragma("unroll") for (int k = 0; k < 2; ++k) dst[m][k] = *(const LAS bf16x8*)(lds + PG8_SA(b, h) + aoff + m * 2048 + k * 1024); } while (0)
; #define PG8_LDB(dst, b, h) do { _Pragma("unroll") for (int n = 0; n < 2; ++n) _Pragma("unroll") for (int k = 0; k < 2; ++k) dst[n][k] = *(const LAS bf16x8*)(lds + PG8_SB(b, h) + boff + n * 2048 + k * 1024); } while (0)
; #define PG8_MMA(ai, bj, At, Bt) do { __builtin_amdgcn_s_setprio(1); _Pragma("unroll") for (int m = 0; m < 4; ++m) _Pragma("unroll") for (int n = 0; n < 2; ++n) _Pragma("unroll") for (int k = 0; k < 2; ++k) \
;     acc[ai][bj][m][n] = __builtin_amdgcn_mfma_f32_16x16x32_bf16(Bt[n][k], At[m][k], acc[ai][bj][m][n], 0, 0, 0); __builtin_amdgcn_s_setprio(0); } while (0)
; #define PG8_WAIT_V(n) asm volatile("s_waitcnt vmcnt(" #n ")" ::: "memory")
; #define PG8_WAIT_L(n) asm volatile("s_waitcnt lgkmcnt(" #n ")" ::: "memory")
; #define PG8_BAR __builtin_amdgcn_s_barrier()
; #define PG8_SCHED __builtin_amdgcn_sched_barrier(0)
; DI void gemm_phase(const GemmDesc& g, LAS unsigned char* lds) {
;     ...
;       PG8_LDB(B0, 1, 0); PG8_LDB(B1, 1, 1); PG8_SCHED; PG8_LDA(At, 1, 0); PG8_STAGE(PG8_SA(0, 1), a2 + hstep, voffA);
;       PG8_WAIT_V(8); PG8_WAIT_L(0); PG8_BAR; PG8_MMA(0, 0, At, B0); PG8_MMA(0, 1, At, B1); PG8_BAR; PG8_SCHED;
;       PG8_LDA(At, 1, 1); PG8_STAGE(PG8_SB(1, 0), b3, voffB); PG8_STAGE(PG8_SB(1, 1), b3 + hstep, voffB); PG8_STAGE(PG8_SA(1, 0), a3, voffA);
;       PG8_WAIT_V(8); PG8_WAIT_L(0); PG8_BAR; PG8_MMA(1, 0, At, B0); PG8_MMA(1, 1, At, B1); PG8_BAR; PG8_SCHED;
;     }
;     if (wr == 0) PG8_BAR;
	ds_read_b128 v[128:131], v250 offset:32768
	ds_read_b128 v[132:135], v250 offset:33792
	ds_read_b128 v[136:139], v250 offset:34816
	ds_read_b128 v[140:143], v250 offset:35840
	ds_read_b128 v[164:167], v250 offset:49152
	ds_read_b128 v[168:171], v250 offset:50176
	ds_read_b128 v[172:175], v250 offset:51200
	ds_read_b128 v[176:179], v250 offset:52224
	s_add_u32 s44, s44, s20
	s_addc_u32 s45, s45, s21
	s_mov_b32 m0, s61
	ds_read_b128 v[180:183], v228 offset:32768
	ds_read_b128 v[184:187], v228 offset:33792
	ds_read_b128 v[188:191], v228 offset:34816
	ds_read_b128 v[192:195], v228 offset:35840
	ds_read_b128 v[196:199], v228 offset:36864
	ds_read_b128 v[200:203], v228 offset:37888
	ds_read_b128 v[230:233], v228 offset:38912
	ds_read_b128 v[234:237], v228 offset:39936
	global_load_lds_dwordx4 v150, s[44:45]
	s_mov_b32 m0, s93
	s_nop 0
	global_load_lds_dwordx4 v154, s[44:45]
	s_add_i32 s49, 0, 0x18000
	s_add_i32 s51, 0, 0x1c000
	s_waitcnt vmcnt(8)
	s_waitcnt lgkmcnt(0)
	s_barrier
	s_setprio 1
	s_waitcnt lgkmcnt(0)
	v_mfma_f32_16x16x32_bf16 v[124:127], v[128:131], v[180:183], v[124:127]
	v_mfma_f32_16x16x32_bf16 v[120:123], v[136:139], v[180:183], v[120:123]
	v_mfma_f32_16x16x32_bf16 v[116:119], v[128:131], v[188:191], v[116:119]
	v_mfma_f32_16x16x32_bf16 v[112:115], v[136:139], v[188:191], v[112:115]
	v_mfma_f32_16x16x32_bf16 v[108:111], v[128:131], v[196:199], v[108:111]
	v_mfma_f32_16x16x32_bf16 v[104:107], v[136:139], v[196:199], v[104:107]
	v_mfma_f32_16x16x32_bf16 v[100:103], v[128:131], v[230:233], v[100:103]
	v_mfma_f32_16x16x32_bf16 v[96:99], v[136:139], v[230:233], v[96:99]
	v_mfma_f32_16x16x32_bf16 v[124:127], v[132:135], v[184:187], v[124:127]
	v_mfma_f32_16x16x32_bf16 v[120:123], v[140:143], v[184:187], v[120:123]
	v_mfma_f32_16x16x32_bf16 v[116:119], v[132:135], v[192:195], v[116:119]
	v_mfma_f32_16x16x32_bf16 v[112:115], v[140:143], v[192:195], v[112:115]
	v_mfma_f32_16x16x32_bf16 v[108:111], v[132:135], v[200:203], v[108:111]
	v_mfma_f32_16x16x32_bf16 v[104:107], v[140:143], v[200:203], v[104:107]
	v_mfma_f32_16x16x32_bf16 v[100:103], v[132:135], v[234:237], v[100:103]
	v_mfma_f32_16x16x32_bf16 v[96:99], v[140:143], v[234:237], v[96:99]
	v_mfma_f32_16x16x32_bf16 v[60:63], v[164:167], v[180:183], v[60:63]
	v_mfma_f32_16x16x32_bf16 v[56:59], v[172:175], v[180:183], v[56:59]
	v_mfma_f32_16x16x32_bf16 v[52:55], v[164:167], v[188:191], v[52:55]
	v_mfma_f32_16x16x32_bf16 v[48:51], v[172:175], v[188:191], v[48:51]
	v_mfma_f32_16x16x32_bf16 v[44:47], v[164:167], v[196:199], v[44:47]
	v_mfma_f32_16x16x32_bf16 v[40:43], v[172:175], v[196:199], v[40:43]
	v_mfma_f32_16x16x32_bf16 v[36:39], v[164:167], v[230:233], v[36:39]
	v_mfma_f32_16x16x32_bf16 v[32:35], v[172:175], v[230:233], v[32:35]
	v_mfma_f32_16x16x32_bf16 v[60:63], v[168:171], v[184:187], v[60:63]
	v_mfma_f32_16x16x32_bf16 v[56:59], v[176:179], v[184:187], v[56:59]
	v_mfma_f32_16x16x32_bf16 v[52:55], v[168:171], v[192:195], v[52:55]
	v_mfma_f32_16x16x32_bf16 v[48:51], v[176:179], v[192:195], v[48:51]
	v_mfma_f32_16x16x32_bf16 v[44:47], v[168:171], v[200:203], v[44:47]
	v_mfma_f32_16x16x32_bf16 v[40:43], v[176:179], v[200:203], v[40:43]
	v_mfma_f32_16x16x32_bf16 v[36:39], v[168:171], v[234:237], v[36:39]
	v_mfma_f32_16x16x32_bf16 v[32:35], v[176:179], v[234:237], v[32:35]
	s_setprio 0
	s_barrier
	s_add_i32 s44, s49, s72
	s_sub_i32 m0, s44, 0x80
	ds_read_b128 v[180:183], v228 offset:49152
	ds_read_b128 v[184:187], v228 offset:50176
	ds_read_b128 v[188:191], v228 offset:51200
	ds_read_b128 v[192:195], v228 offset:52224
	ds_read_b128 v[196:199], v228 offset:53248
	ds_read_b128 v[200:203], v228 offset:54272
	ds_read_b128 v[230:233], v228 offset:55296
	ds_read_b128 v[234:237], v228 offset:56320
	global_load_lds_dwordx4 v152, s[98:99] offset:128
	s_add_i32 m0, s44, 0x1f80
	s_add_i32 s44, s51, s72
	global_load_lds_dwordx4 v156, s[98:99] offset:128
	s_sub_i32 m0, s44, 0x80
	s_nop 0
	global_load_lds_dwordx4 v152, s[86:87] offset:128
	s_add_i32 m0, s44, 0x1f80
	s_nop 0
	global_load_lds_dwordx4 v156, s[86:87] offset:128
	s_sub_i32 m0, s95, 0x80
	s_nop 0
	global_load_lds_dwordx4 v150, s[100:101] offset:128
	s_sub_i32 m0, s96, 0x80
	s_nop 0
	global_load_lds_dwordx4 v154, s[100:101] offset:128
	s_add_u32 s46, s46, 0x100
	s_addc_u32 s47, s47, 0
	s_add_u32 s26, s26, 0x100
	s_addc_u32 s27, s27, 0
	s_waitcnt vmcnt(8)
	s_waitcnt lgkmcnt(0)
	s_barrier
	s_setprio 1
	s_waitcnt lgkmcnt(0)
	v_mfma_f32_16x16x32_bf16 v[92:95], v[128:131], v[180:183], v[92:95]
	v_mfma_f32_16x16x32_bf16 v[88:91], v[136:139], v[180:183], v[88:91]
	v_mfma_f32_16x16x32_bf16 v[84:87], v[128:131], v[188:191], v[84:87]
	v_mfma_f32_16x16x32_bf16 v[80:83], v[136:139], v[188:191], v[80:83]
	v_mfma_f32_16x16x32_bf16 v[76:79], v[128:131], v[196:199], v[76:79]
	v_mfma_f32_16x16x32_bf16 v[72:75], v[136:139], v[196:199], v[72:75]
	v_mfma_f32_16x16x32_bf16 v[68:71], v[128:131], v[230:233], v[68:71]
	v_mfma_f32_16x16x32_bf16 v[64:67], v[136:139], v[230:233], v[64:67]
	v_mfma_f32_16x16x32_bf16 v[92:95], v[132:135], v[184:187], v[92:95]
	v_mfma_f32_16x16x32_bf16 v[88:91], v[140:143], v[184:187], v[88:91]
	v_mfma_f32_16x16x32_bf16 v[84:87], v[132:135], v[192:195], v[84:87]
	v_mfma_f32_16x16x32_bf16 v[80:83], v[140:143], v[192:195], v[80:83]
	v_mfma_f32_16x16x32_bf16 v[76:79], v[132:135], v[200:203], v[76:79]
	v_mfma_f32_16x16x32_bf16 v[72:75], v[140:143], v[200:203], v[72:75]
	v_mfma_f32_16x16x32_bf16 v[68:71], v[132:135], v[234:237], v[68:71]
	v_mfma_f32_16x16x32_bf16 v[64:67], v[140:143], v[234:237], v[64:67]
	v_mfma_f32_16x16x32_bf16 v[28:31], v[164:167], v[180:183], v[28:31]
	v_mfma_f32_16x16x32_bf16 v[24:27], v[172:175], v[180:183], v[24:27]
	v_mfma_f32_16x16x32_bf16 v[20:23], v[164:167], v[188:191], v[20:23]
	v_mfma_f32_16x16x32_bf16 v[16:19], v[172:175], v[188:191], v[16:19]
	v_mfma_f32_16x16x32_bf16 v[12:15], v[164:167], v[196:199], v[12:15]
	v_mfma_f32_16x16x32_bf16 v[8:11], v[172:175], v[196:199], v[8:11]
	v_mfma_f32_16x16x32_bf16 v[4:7], v[164:167], v[230:233], v[4:7]
	v_mfma_f32_16x16x32_bf16 v[0:3], v[172:175], v[230:233], v[0:3]
	v_mfma_f32_16x16x32_bf16 v[28:31], v[168:171], v[184:187], v[28:31]
	v_mfma_f32_16x16x32_bf16 v[24:27], v[176:179], v[184:187], v[24:27]
	v_mfma_f32_16x16x32_bf16 v[20:23], v[168:171], v[192:195], v[20:23]
	v_mfma_f32_16x16x32_bf16 v[16:19], v[176:179], v[192:195], v[16:19]
	v_mfma_f32_16x16x32_bf16 v[12:15], v[168:171], v[200:203], v[12:15]
	v_mfma_f32_16x16x32_bf16 v[8:11], v[176:179], v[200:203], v[8:11]
	v_mfma_f32_16x16x32_bf16 v[4:7], v[168:171], v[234:237], v[4:7]
	v_mfma_f32_16x16x32_bf16 v[0:3], v[176:179], v[234:237], v[0:3]
	s_setprio 0
	s_barrier
	s_cmp_ge_u32 s48, s82
	s_mov_b32 s44, s48
	s_cbranch_scc0 .LBB0_132
	s_and_b64 vcc, exec, s[56:57]
	s_cbranch_vccz .LBB0_135
	s_barrier

; __global__ void __launch_bounds__(512, 2) mega(Params p) {
	.amdhsa_kernel _Z4mega6Params
		.amdhsa_group_segment_fixed_size 0
		.amdhsa_private_segment_fixed_size 0
		.amdhsa_kernarg_size 448
		.amdhsa_user_sgpr_count 2
		.amdhsa_user_sgpr_dispatch_ptr 0
		.amdhsa_user_sgpr_queue_ptr 0
		.amdhsa_user_sgpr_kernarg_segment_ptr 1
		.amdhsa_user_sgpr_dispatch_id 0
		.amdhsa_user_sgpr_kernarg_preload_length 0
		.amdhsa_user_sgpr_kernarg_preload_offset 0
		.amdhsa_user_sgpr_private_segment_size 0
		.amdhsa_uses_dynamic_stack 0
		.amdhsa_enable_private_segment 0
		.amdhsa_system_sgpr_workgroup_id_x 1
		.amdhsa_system_sgpr_workgroup_id_y 0
		.amdhsa_system_sgpr_workgroup_id_z 0
		.amdhsa_system_sgpr_workgroup_info 0
		.amdhsa_system_vgpr_workitem_id 2
		.amdhsa_next_free_vgpr 256
		.amdhsa_next_free_sgpr 102
		.amdhsa_accum_offset 256
		.amdhsa_reserve_vcc 1
		.amdhsa_float_round_mode_32 0
		.amdhsa_float_round_mode_16_64 0
		.amdhsa_float_denorm_mode_32 3
		.amdhsa_float_denorm_mode_16_64 3
		.amdhsa_dx10_clamp 1
		.amdhsa_ieee_mode 1
		.amdhsa_fp16_overflow 0
		.amdhsa_tg_split 0
		.amdhsa_exception_fp_ieee_invalid_op 0
		.amdhsa_exception_fp_denorm_src 0
		.amdhsa_exception_fp_ieee_div_zero 0
		.amdhsa_exception_fp_ieee_overflow 0
		.amdhsa_exception_fp_ieee_underflow 0
		.amdhsa_exception_fp_ieee_inexact 0
		.amdhsa_exception_int_div_zero 0
	.end_amdhsa_kernel

; __global__ void __launch_bounds__(512, 2) mega(Params p) {
amdhsa.kernels:
  - .agpr_count:     0
    .args:
      - .offset:         0
        .size:           192
        .value_kind:     by_value
      - .offset:         192
        .size:           4
        .value_kind:     hidden_block_count_x
      - .offset:         196
        .size:           4
        .value_kind:     hidden_block_count_y
      - .offset:         200
        .size:           4
        .value_kind:     hidden_block_count_z
      - .offset:         204
        .size:           2
        .value_kind:     hidden_group_size_x
      - .offset:         206
        .size:           2
        .value_kind:     hidden_group_size_y
      - .offset:         208
        .size:           2
        .value_kind:     hidden_group_size_z
      - .offset:         210
        .size:           2
        .value_kind:     hidden_remainder_x
      - .offset:         212
        .size:           2
        .value_kind:     hidden_remainder_y
      - .offset:         214
        .size:           2
        .value_kind:     hidden_remainder_z
      - .offset:         232
        .size:           8
        .value_kind:     hidden_global_offset_x
      - .offset:         240
        .size:           8
        .value_kind:     hidden_global_offset_y
      - .offset:         248
        .size:           8
        .value_kind:     hidden_global_offset_z
      - .offset:         256
        .size:           2
        .value_kind:     hidden_grid_dims
      - .offset:         280
        .size:           8
        .value_kind:     hidden_multigrid_sync_arg
      - .offset:         312
        .size:           4
        .value_kind:     hidden_dynamic_lds_size
    .group_segment_fixed_size: 0
    .kernarg_segment_align: 8
    .kernarg_segment_size: 448
    .language:       OpenCL C
    .language_version:
      - 2
      - 0
    .max_flat_workgroup_size: 512
    .name:           _Z4mega6Params
    .private_segment_fixed_size: 0
    .sgpr_count:     108
    .sgpr_spill_count: 183
    .symbol:         _Z4mega6Params.kd
    .uniform_work_group_size: 1
    .uses_dynamic_stack: false
    .vgpr_count:     256
    .vgpr_spill_count: 0
    .wavefront_size: 64
